# baseline (speedup 1.0000x reference)
.LBB0_397:
	s_or_b64 exec, exec, s[0:1]
	s_waitcnt lgkmcnt(0)
	s_barrier
	ds_read_b32 v0, v165
	s_movk_i32 s14, 0xff
	s_xor_b64 s[0:1], s[76:77], -1
	s_waitcnt lgkmcnt(0)
	v_cmp_lt_i32_e64 s[38:39], s14, v0
	v_readfirstlane_b32 s35, v0
	s_and_b64 vcc, exec, s[38:39]
	s_cbranch_vccnz .LBB0_392
	s_cmpk_lt_i32 s35, 64
	s_cbranch_scc1 .Lremap_done
	s_sub_i32 s100, s35, 64
	s_mul_i32 s101, s100, 0xab
	s_lshr_b32 s101, s101, 9
	s_mul_i32 s98, s101, 3
	s_sub_i32 s100, s100, s98
	s_cmp_eq_u32 s100, 0
	s_cbranch_scc1 .Lremap_attn
	s_lshl_b32 s98, s101, 1
	s_add_i32 s35, s98, s100
	s_addk_i32 s35, 0x7f
	s_branch .Lremap_done
.Lremap_attn:
	s_add_i32 s35, s101, 64
.Lremap_done:
	s_mov_b64 s[14:15], -1
	s_cmpk_gt_i32 s35, 0x7f
	s_mov_b64 s[40:41], -1
	s_cbranch_scc0 .LBB0_476
	s_andn2_b64 vcc, exec, s[0:1]
	s_cbranch_vccnz .LBB0_405
	s_and_saveexec_b64 s[0:1], s[42:43]
	s_cbranch_execz .LBB0_404
	global_load_dword v0, v1, s[70:71] sc1
	s_waitcnt vmcnt(0)
	v_cmp_lt_u32_e32 vcc, 64, v0
	s_cbranch_vccnz .LBB0_403

.LBB0_409:
	s_or_b64 exec, exec, s[0:1]
	s_lshl_b32 s0, s50, 15
	v_ashrrev_i32_e32 v132, 4, v129
	s_add_u32 s40, s61, s0
	v_lshlrev_b32_e32 v134, 3, v129
	s_waitcnt vmcnt(2)
	v_add_u32_e32 v83, s92, v132
	s_addc_u32 s41, s63, 0
	v_and_b32_e32 v135, 0x78, v134
	s_lshl_b32 s1, s52, 7
	v_max_i32_e32 v6, 2, v83
	v_or_b32_e32 v4, s1, v135
	v_lshlrev_b32_e32 v98, 1, v135
	v_mov_b32_e32 v99, v1
	v_mov_b64_e32 v[100:101], s[22:23]
	v_add_u32_e32 v6, -2, v6
	v_lshl_add_u64 v[114:115], s[40:41], 0, v[98:99]
	v_lshlrev_b32_e32 v102, 1, v4
	v_mov_b32_e32 v103, v1
	v_mad_u64_u32 v[6:7], s[40:41], v6, s89, v[100:101]
	v_lshl_add_u64 v[10:11], v[6:7], 0, v[102:103]
	v_max_i32_e32 v6, 1, v83
	v_add_u32_e32 v6, -1, v6
	v_max_i32_e32 v2, 3, v83
	v_mad_u64_u32 v[6:7], s[40:41], v6, s89, v[100:101]
	v_add_u32_e32 v2, -3, v2
	v_lshl_add_u64 v[8:9], v[6:7], 0, v[102:103]
	v_max_i32_e32 v6, 0, v83
	v_mad_u64_u32 v[2:3], s[40:41], v2, s89, v[100:101]
	v_mad_u64_u32 v[6:7], s[40:41], v6, s89, v[100:101]
	v_lshl_add_u64 v[12:13], v[2:3], 0, v[102:103]
	v_lshl_add_u64 v[6:7], v[6:7], 0, v[102:103]
	v_lshlrev_b32_e32 v0, 2, v4
	global_load_dwordx4 v[2:5], v[12:13], off offset:832
	global_load_dwordx4 v[20:23], v[10:11], off offset:832
	global_load_dwordx4 v[28:31], v[8:9], off offset:832
	global_load_dwordx4 v[40:43], v[6:7], off offset:832
	v_cmp_lt_i32_e32 vcc, 2, v83
	v_lshl_add_u64 v[14:15], s[64:65], 0, v[0:1]
	s_movk_i32 s0, 0x1000
	v_cndmask_b32_e64 v82, 0, 1.0, vcc
	v_cmp_lt_i32_e32 vcc, 1, v83
	s_mov_b64 s[44:45], 0x1000
	v_lshl_add_u64 v[26:27], v[14:15], 0, s[44:45]
	v_cndmask_b32_e64 v84, 0, 1.0, vcc
	v_cmp_lt_i32_e32 vcc, 0, v83
	s_mov_b64 s[44:45], 0x2000
	v_lshl_add_u64 v[38:39], v[14:15], 0, s[44:45]
	v_cndmask_b32_e64 v86, 0, 1.0, vcc
	v_cmp_lt_i32_e32 vcc, -1, v83
	s_mov_b64 s[44:45], 0x3000
	v_lshl_add_u64 v[16:17], v[14:15], 0, s[44:45]
	v_cndmask_b32_e64 v88, 0, 1.0, vcc
	s_mov_b64 s[44:45], 0x1800
	v_lshl_add_u64 v[34:35], v[14:15], 0, s[44:45]
	s_mov_b64 s[44:45], 0x2800
	v_lshl_add_u64 v[66:67], v[14:15], 0, s[44:45]
	v_lshl_add_u64 v[78:79], v[14:15], 0, s[2:3]
	s_lshl_b32 s16, s52, 8
	v_and_b32_e32 v133, 31, v129
	v_lshrrev_b32_e32 v130, 5, v128
	s_waitcnt vmcnt(3)
	v_lshlrev_b32_e32 v36, 16, v2
	v_and_b32_e32 v37, 0xffff0000, v2
	v_lshlrev_b32_e32 v80, 16, v3
	v_and_b32_e32 v81, 0xffff0000, v3
	v_lshlrev_b32_e32 v52, 16, v4
	v_and_b32_e32 v53, 0xffff0000, v4
	v_lshlrev_b32_e32 v18, 16, v5
	v_and_b32_e32 v19, 0xffff0000, v5
	s_waitcnt vmcnt(2)
	v_lshlrev_b32_e32 v54, 16, v20
	v_and_b32_e32 v55, 0xffff0000, v20
	v_lshlrev_b32_e32 v92, 16, v21
	v_and_b32_e32 v93, 0xffff0000, v21
	v_lshlrev_b32_e32 v72, 16, v22
	v_and_b32_e32 v73, 0xffff0000, v22
	v_lshlrev_b32_e32 v20, 16, v23
	v_and_b32_e32 v21, 0xffff0000, v23
	s_waitcnt vmcnt(1)
	v_lshlrev_b32_e32 v76, 16, v30
	v_and_b32_e32 v77, 0xffff0000, v30
	v_lshlrev_b32_e32 v50, 16, v31
	v_and_b32_e32 v51, 0xffff0000, v31
	s_waitcnt vmcnt(0)
	v_lshlrev_b32_e32 v90, 16, v42
	v_and_b32_e32 v91, 0xffff0000, v42
	v_lshlrev_b32_e32 v70, 16, v43
	v_and_b32_e32 v71, 0xffff0000, v43
	global_load_dwordx4 v[2:5], v0, s[66:67] offset:16
	global_load_dwordx4 v[30:33], v0, s[66:67]
	global_load_dwordx4 v[22:25], v0, s[64:65] offset:16
	global_load_dwordx4 v[42:45], v0, s[64:65]
	v_lshlrev_b32_e32 v58, 16, v28
	v_and_b32_e32 v59, 0xffff0000, v28
	v_lshlrev_b32_e32 v94, 16, v29
	v_and_b32_e32 v95, 0xffff0000, v29
	v_pk_mul_f32 v[28:29], v[82:83], v[36:37] op_sel_hi:[0,1]
	v_add_co_u32_e32 v36, vcc, s0, v14
	v_lshlrev_b32_e32 v96, 16, v40
	s_nop 0
	v_addc_co_u32_e32 v37, vcc, 0, v15, vcc
	v_add_co_u32_e32 v68, vcc, s93, v14
	v_and_b32_e32 v97, 0xffff0000, v40
	s_nop 0
	v_addc_co_u32_e32 v69, vcc, 0, v15, vcc
	v_lshlrev_b32_e32 v104, 16, v41
	v_and_b32_e32 v105, 0xffff0000, v41
	v_pk_mul_f32 v[54:55], v[84:85], v[54:55] op_sel_hi:[0,1]
	s_movk_i32 s0, 0x3000
	v_add_co_u32_e32 v74, vcc, s0, v14
	v_pk_mul_f32 v[58:59], v[86:87], v[58:59] op_sel_hi:[0,1]
	s_nop 0
	v_addc_co_u32_e32 v75, vcc, 0, v15, vcc
	v_pk_mul_f32 v[14:15], v[88:89], v[96:97] op_sel_hi:[0,1]
	v_pk_mul_f32 v[18:19], v[82:83], v[18:19] op_sel_hi:[0,1]
	v_pk_mul_f32 v[20:21], v[84:85], v[20:21] op_sel_hi:[0,1]
	s_lshr_b32 s0, s94, 1
	s_waitcnt vmcnt(1)
	v_pk_fma_f32 v[18:19], v[18:19], v[24:25], v[4:5]
	s_waitcnt vmcnt(0)
	v_pk_fma_f32 v[40:41], v[28:29], v[42:43], v[30:31]
	global_load_dwordx4 v[46:49], v[68:69], off offset:-4096
	s_nop 0
	global_load_dwordx4 v[26:29], v[26:27], off offset:16
	s_waitcnt vmcnt(1)
	v_pk_fma_f32 v[60:61], v[54:55], v[46:47], v[40:41]
	global_load_dwordx4 v[54:57], v[68:69], off
	s_nop 0
	global_load_dwordx4 v[38:41], v[38:39], off offset:16
	s_waitcnt vmcnt(2)
	v_pk_fma_f32 v[18:19], v[20:21], v[28:29], v[18:19]
	v_pk_mul_f32 v[20:21], v[86:87], v[50:51] op_sel_hi:[0,1]
	s_waitcnt vmcnt(1)
	v_pk_fma_f32 v[106:107], v[58:59], v[54:55], v[60:61]
	global_load_dwordx4 v[62:65], v[74:75], off
	global_load_dwordx4 v[58:61], v[16:17], off offset:16
	s_waitcnt vmcnt(2)
	v_pk_fma_f32 v[18:19], v[20:21], v[40:41], v[18:19]
	v_pk_mul_f32 v[20:21], v[88:89], v[70:71] op_sel_hi:[0,1]
	s_waitcnt vmcnt(1)
	v_pk_fma_f32 v[14:15], v[14:15], v[62:63], v[106:107]
	s_nop 0
	v_mul_f32_e32 v16, 0xbfb8aa3b, v14
	v_mul_f32_e32 v17, 0xbfb8aa3b, v15
	v_exp_f32_e32 v16, v16
	v_exp_f32_e32 v17, v17
	s_waitcnt vmcnt(0)
	v_pk_fma_f32 v[18:19], v[20:21], v[60:61], v[18:19]
	v_add_f32_e32 v16, 1.0, v16
	v_add_f32_e32 v17, 1.0, v17
	v_rcp_f32_e32 v16, v16
	v_rcp_f32_e32 v17, v17
	s_nop 0
	v_pk_mul_f32 v[14:15], v[14:15], v[16:17]
	v_pk_mul_f32 v[16:17], v[82:83], v[80:81] op_sel_hi:[0,1]
	v_pk_fma_f32 v[16:17], v[16:17], v[44:45], v[32:33]
	v_pk_mul_f32 v[80:81], v[84:85], v[92:93] op_sel_hi:[0,1]
	v_pk_fma_f32 v[16:17], v[80:81], v[48:49], v[16:17]
	v_pk_mul_f32 v[80:81], v[86:87], v[94:95] op_sel_hi:[0,1]
	v_pk_fma_f32 v[16:17], v[80:81], v[56:57], v[16:17]
	v_pk_mul_f32 v[80:81], v[88:89], v[104:105] op_sel_hi:[0,1]
	v_pk_mul_f32 v[14:15], v[14:15], s[60:61] op_sel_hi:[1,0]
	v_pk_fma_f32 v[16:17], v[80:81], v[64:65], v[16:17]
	v_cvt_pk_bf16_f32 v14, v14, v15
	v_mul_f32_e32 v15, 0xbfb8aa3b, v16
	v_exp_f32_e32 v15, v15
	s_nop 0
	v_add_f32_e32 v15, 1.0, v15
	v_rcp_f32_e32 v80, v15
	v_mul_f32_e32 v15, 0xbfb8aa3b, v17
	v_exp_f32_e32 v15, v15
	s_nop 0
	v_add_f32_e32 v15, 1.0, v15
	v_rcp_f32_e32 v81, v15
	s_nop 0
	v_pk_mul_f32 v[16:17], v[16:17], v[80:81]
	s_nop 0
	v_pk_mul_f32 v[16:17], v[16:17], s[60:61] op_sel_hi:[1,0]
	s_nop 0
	v_cvt_pk_bf16_f32 v15, v16, v17
	v_pk_mul_f32 v[16:17], v[82:83], v[52:53] op_sel_hi:[0,1]
	v_pk_fma_f32 v[16:17], v[16:17], v[22:23], v[2:3]
	v_pk_mul_f32 v[52:53], v[84:85], v[72:73] op_sel_hi:[0,1]
	v_pk_fma_f32 v[16:17], v[52:53], v[26:27], v[16:17]
	v_pk_mul_f32 v[52:53], v[86:87], v[76:77] op_sel_hi:[0,1]
	v_pk_fma_f32 v[16:17], v[52:53], v[38:39], v[16:17]
	v_pk_mul_f32 v[52:53], v[88:89], v[90:91] op_sel_hi:[0,1]
	v_pk_fma_f32 v[16:17], v[52:53], v[58:59], v[16:17]
	v_mad_u64_u32 v[90:91], s[40:41], v132, s28, v[98:99]
	v_mul_f32_e32 v52, 0xbfb8aa3b, v16
	v_mul_f32_e32 v53, 0xbfb8aa3b, v17
	v_exp_f32_e32 v52, v52
	v_exp_f32_e32 v53, v53
	v_add_f32_e32 v52, 1.0, v52
	v_add_f32_e32 v53, 1.0, v53
	v_rcp_f32_e32 v52, v52
	v_rcp_f32_e32 v53, v53
	s_nop 0
	v_pk_mul_f32 v[16:17], v[16:17], v[52:53]
	s_nop 0
	v_pk_mul_f32 v[16:17], v[16:17], s[60:61] op_sel_hi:[1,0]
	s_nop 0
	v_cvt_pk_bf16_f32 v16, v16, v17
	v_mul_f32_e32 v17, 0xbfb8aa3b, v18
	v_exp_f32_e32 v17, v17
	s_nop 0
	v_add_f32_e32 v17, 1.0, v17
	v_rcp_f32_e32 v20, v17
	v_mul_f32_e32 v17, 0xbfb8aa3b, v19
	v_exp_f32_e32 v17, v17
	s_nop 0
	v_add_f32_e32 v17, 1.0, v17
	v_rcp_f32_e32 v21, v17
	s_nop 0
	v_pk_mul_f32 v[18:19], v[18:19], v[20:21]
	s_nop 0
	v_pk_mul_f32 v[18:19], v[18:19], s[60:61] op_sel_hi:[1,0]
	s_nop 0
	v_cvt_pk_bf16_f32 v17, v18, v19
	ds_write_b128 v90, v[14:17]
	global_load_dwordx4 v[12:15], v[12:13], off offset:1856
	s_nop 0
	global_load_dwordx4 v[16:19], v[10:11], off offset:1856
	s_nop 0
	global_load_dwordx4 v[8:11], v[8:9], off offset:1856
	s_nop 0
	global_load_dwordx4 v[50:53], v[6:7], off offset:1856
	s_waitcnt vmcnt(3)
	v_lshlrev_b32_e32 v70, 16, v12
	v_and_b32_e32 v71, 0xffff0000, v12
	v_lshlrev_b32_e32 v112, 16, v13
	v_and_b32_e32 v113, 0xffff0000, v13
	v_lshlrev_b32_e32 v104, 16, v14
	v_and_b32_e32 v105, 0xffff0000, v14
	v_lshlrev_b32_e32 v92, 16, v15
	v_and_b32_e32 v93, 0xffff0000, v15
	s_waitcnt vmcnt(2)
	v_lshlrev_b32_e32 v72, 16, v16
	v_and_b32_e32 v73, 0xffff0000, v16
	v_lshlrev_b32_e32 v118, 16, v17
	v_and_b32_e32 v119, 0xffff0000, v17
	v_lshlrev_b32_e32 v108, 16, v18
	v_and_b32_e32 v109, 0xffff0000, v18
	v_lshlrev_b32_e32 v94, 16, v19
	v_and_b32_e32 v95, 0xffff0000, v19
	s_waitcnt vmcnt(1)
	v_lshlrev_b32_e32 v76, 16, v8
	v_and_b32_e32 v77, 0xffff0000, v8
	v_lshlrev_b32_e32 v120, 16, v9
	v_and_b32_e32 v121, 0xffff0000, v9
	v_lshlrev_b32_e32 v110, 16, v10
	v_and_b32_e32 v111, 0xffff0000, v10
	v_lshlrev_b32_e32 v96, 16, v11
	v_and_b32_e32 v97, 0xffff0000, v11
	global_load_dwordx4 v[6:9], v0, s[66:67] offset:2064
	global_load_dwordx4 v[14:17], v0, s[66:67] offset:2048
	global_load_dwordx4 v[10:13], v0, s[64:65] offset:2064
	global_load_dwordx4 v[18:21], v0, s[64:65] offset:2048
	s_waitcnt vmcnt(4)
	v_lshlrev_b32_e32 v124, 16, v50
	v_and_b32_e32 v125, 0xffff0000, v50
	v_lshlrev_b32_e32 v122, 16, v51
	v_and_b32_e32 v123, 0xffff0000, v51
	v_pk_mul_f32 v[50:51], v[82:83], v[70:71] op_sel_hi:[0,1]
	v_lshlrev_b32_e32 v116, 16, v52
	v_and_b32_e32 v117, 0xffff0000, v52
	v_lshlrev_b32_e32 v106, 16, v53
	v_and_b32_e32 v107, 0xffff0000, v53
	v_pk_mul_f32 v[72:73], v[84:85], v[72:73] op_sel_hi:[0,1]
	v_pk_mul_f32 v[76:77], v[86:87], v[76:77] op_sel_hi:[0,1]
	v_pk_mul_f32 v[124:125], v[88:89], v[124:125] op_sel_hi:[0,1]
	v_pk_mul_f32 v[112:113], v[82:83], v[112:113] op_sel_hi:[0,1]
	v_pk_mul_f32 v[118:119], v[84:85], v[118:119] op_sel_hi:[0,1]
	v_pk_mul_f32 v[104:105], v[82:83], v[104:105] op_sel_hi:[0,1]
	v_pk_mul_f32 v[108:109], v[84:85], v[108:109] op_sel_hi:[0,1]
	v_pk_mul_f32 v[92:93], v[82:83], v[92:93] op_sel_hi:[0,1]
	v_pk_mul_f32 v[84:85], v[84:85], v[94:95] op_sel_hi:[0,1]
	v_mad_i64_i32 v[82:83], s[40:41], v83, s89, v[100:101]
	v_lshl_add_u64 v[82:83], v[82:83], 0, s[16:17]
	v_lshl_add_u64 v[82:83], v[82:83], 0, v[98:99]
	s_waitcnt vmcnt(1)
	v_pk_fma_f32 v[104:105], v[104:105], v[10:11], v[6:7]
	s_waitcnt vmcnt(0)
	v_pk_fma_f32 v[70:71], v[50:51], v[18:19], v[14:15]
	global_load_dwordx4 v[50:53], v[36:37], off offset:2048
	s_nop 0
	global_load_dwordx4 v[34:37], v[34:35], off offset:16
	v_pk_fma_f32 v[112:113], v[112:113], v[20:21], v[16:17]
	v_pk_fma_f32 v[92:93], v[92:93], v[12:13], v[8:9]
	s_waitcnt vmcnt(1)
	v_pk_fma_f32 v[80:81], v[72:73], v[50:51], v[70:71]
	global_load_dwordx4 v[70:73], v[68:69], off offset:2048
	s_nop 0
	global_load_dwordx4 v[66:69], v[66:67], off offset:16
	v_pk_fma_f32 v[112:113], v[118:119], v[52:53], v[112:113]
	v_pk_mul_f32 v[118:119], v[86:87], v[120:121] op_sel_hi:[0,1]
	s_waitcnt vmcnt(2)
	v_pk_fma_f32 v[104:105], v[108:109], v[34:35], v[104:105]
	v_pk_mul_f32 v[108:109], v[86:87], v[110:111] op_sel_hi:[0,1]
	v_pk_fma_f32 v[84:85], v[84:85], v[36:37], v[92:93]
	v_pk_mul_f32 v[86:87], v[86:87], v[96:97] op_sel_hi:[0,1]
	s_waitcnt vmcnt(1)
	v_pk_fma_f32 v[126:127], v[76:77], v[70:71], v[80:81]
	global_load_dwordx4 v[74:77], v[74:75], off offset:2048
	s_nop 0
	global_load_dwordx4 v[78:81], v[78:79], off offset:16
	v_pk_fma_f32 v[112:113], v[118:119], v[72:73], v[112:113]
	v_pk_mul_f32 v[118:119], v[88:89], v[122:123] op_sel_hi:[0,1]
	s_waitcnt vmcnt(2)
	v_pk_fma_f32 v[104:105], v[108:109], v[66:67], v[104:105]
	v_pk_mul_f32 v[108:109], v[88:89], v[116:117] op_sel_hi:[0,1]
	v_pk_fma_f32 v[84:85], v[86:87], v[68:69], v[84:85]
	v_pk_mul_f32 v[86:87], v[88:89], v[106:107] op_sel_hi:[0,1]
	v_lshlrev_b32_e32 v116, 7, v132
	v_ashrrev_i32_e32 v117, 31, v116
	s_waitcnt vmcnt(1)
	v_pk_fma_f32 v[124:125], v[124:125], v[74:75], v[126:127]
	s_nop 0
	v_mul_f32_e32 v0, 0xbfb8aa3b, v124
	v_exp_f32_e32 v0, v0
	v_pk_fma_f32 v[112:113], v[118:119], v[76:77], v[112:113]
	s_waitcnt vmcnt(0)
	v_pk_fma_f32 v[104:105], v[108:109], v[78:79], v[104:105]
	v_pk_fma_f32 v[84:85], v[86:87], v[80:81], v[84:85]
	v_add_f32_e32 v0, 1.0, v0
	v_rcp_f32_e32 v126, v0
	v_mul_f32_e32 v0, 0xbfb8aa3b, v125
	v_exp_f32_e32 v0, v0
	s_nop 0
	v_add_f32_e32 v0, 1.0, v0
	v_rcp_f32_e32 v127, v0
	v_mul_f32_e32 v0, 0xbfb8aa3b, v112
	v_exp_f32_e32 v0, v0
	v_pk_mul_f32 v[124:125], v[124:125], v[126:127]
	v_add_f32_e32 v0, 1.0, v0
	v_rcp_f32_e32 v118, v0
	v_mul_f32_e32 v0, 0xbfb8aa3b, v113
	v_exp_f32_e32 v0, v0
	s_nop 0
	v_add_f32_e32 v0, 1.0, v0
	v_rcp_f32_e32 v119, v0
	v_mul_f32_e32 v0, 0xbfb8aa3b, v104
	v_exp_f32_e32 v0, v0
	v_pk_mul_f32 v[112:113], v[112:113], v[118:119]
	v_add_f32_e32 v0, 1.0, v0
	v_rcp_f32_e32 v108, v0
	v_mul_f32_e32 v0, 0xbfb8aa3b, v105
	v_exp_f32_e32 v0, v0
	s_nop 0
	v_add_f32_e32 v0, 1.0, v0
	v_rcp_f32_e32 v109, v0
	v_mul_f32_e32 v0, 0xbfb8aa3b, v84
	v_exp_f32_e32 v0, v0
	v_pk_mul_f32 v[104:105], v[104:105], v[108:109]
	v_add_f32_e32 v0, 1.0, v0
	v_rcp_f32_e32 v86, v0
	v_mul_f32_e32 v0, 0xbfb8aa3b, v85
	v_exp_f32_e32 v0, v0
	s_nop 0
	v_add_f32_e32 v0, 1.0, v0
	v_rcp_f32_e32 v87, v0
	v_lshlrev_b32_e32 v0, 5, v132
	v_bitop3_b32 v122, v0, v135, s95 bitop3:0x6c
	v_pk_mul_f32 v[88:89], v[84:85], v[86:87]
	v_cvt_pk_bf16_f32 v84, v124, v125
	v_cvt_pk_bf16_f32 v85, v112, v113
	v_cvt_pk_bf16_f32 v86, v104, v105
	v_cvt_pk_bf16_f32 v87, v88, v89
	ds_write_b128 v90, v[84:87] offset:17408
	v_and_b32_e32 v84, 0x60, v0
	v_bitop3_b32 v0, v84, v116, v135 bitop3:0xde
	global_load_dwordx4 v[82:85], v[82:83], off offset:2880
	v_lshlrev_b32_e32 v0, 1, v0
	s_waitcnt vmcnt(0)
	ds_write_b128 v0, v[82:85] offset:34816
	v_lshl_add_u64 v[82:83], v[116:117], 1, v[114:115]
	global_load_dwordx4 v[82:85], v[82:83], off
	s_waitcnt vmcnt(0)
	ds_write_b128 v0, v[82:85] offset:51200
	v_add_u32_e32 v0, 0x100, v129
	v_ashrrev_i32_e32 v117, 4, v0
	v_add_u32_e32 v105, s92, v117
	v_max_i32_e32 v0, 3, v105
	v_add_u32_e32 v0, -3, v0
	v_mad_u64_u32 v[82:83], s[40:41], v0, s89, v[100:101]
	v_max_i32_e32 v0, 2, v105
	v_add_u32_e32 v0, -2, v0
	v_mad_u64_u32 v[84:85], s[40:41], v0, s89, v[100:101]
	v_max_i32_e32 v0, 1, v105
	v_lshl_add_u64 v[82:83], v[82:83], 0, v[102:103]
	v_add_u32_e32 v0, -1, v0
	global_load_dwordx4 v[106:109], v[82:83], off offset:832
	v_lshl_add_u64 v[86:87], v[84:85], 0, v[102:103]
	v_mad_u64_u32 v[84:85], s[40:41], v0, s89, v[100:101]
	v_max_i32_e32 v0, 0, v105
	global_load_dwordx4 v[110:113], v[86:87], off offset:832
	v_lshl_add_u64 v[90:91], v[84:85], 0, v[102:103]
	v_mad_u64_u32 v[84:85], s[40:41], v0, s89, v[100:101]
	global_load_dwordx4 v[118:121], v[90:91], off offset:832
	v_lshl_add_u64 v[94:95], v[84:85], 0, v[102:103]
	global_load_dwordx4 v[124:127], v[94:95], off offset:832
	v_cmp_lt_i32_e32 vcc, 2, v105
	s_waitcnt vmcnt(3)
	v_lshlrev_b32_e32 v84, 16, v106
	v_cndmask_b32_e64 v0, 0, 1.0, vcc
	v_and_b32_e32 v85, 0xffff0000, v106
	v_cmp_lt_i32_e32 vcc, 1, v105
	v_pk_mul_f32 v[84:85], v[0:1], v[84:85] op_sel_hi:[0,1]
	s_waitcnt vmcnt(2)
	v_lshlrev_b32_e32 v136, 16, v110
	v_cndmask_b32_e64 v104, 0, 1.0, vcc
	v_and_b32_e32 v137, 0xffff0000, v110
	v_cmp_lt_i32_e32 vcc, 0, v105
	s_waitcnt vmcnt(1)
	v_lshlrev_b32_e32 v140, 16, v118
	v_and_b32_e32 v141, 0xffff0000, v118
	v_cndmask_b32_e64 v106, 0, 1.0, vcc
	v_cmp_lt_i32_e32 vcc, -1, v105
	v_pk_fma_f32 v[84:85], v[42:43], v[84:85], v[30:31]
	v_pk_mul_f32 v[136:137], v[104:105], v[136:137] op_sel_hi:[0,1]
	v_lshlrev_b32_e32 v92, 16, v108
	v_and_b32_e32 v93, 0xffff0000, v108
	v_lshlrev_b32_e32 v142, 16, v119
	v_and_b32_e32 v143, 0xffff0000, v119
	v_cndmask_b32_e64 v108, 0, 1.0, vcc
	s_waitcnt vmcnt(0)
	v_lshlrev_b32_e32 v118, 16, v124
	v_and_b32_e32 v119, 0xffff0000, v124
	v_pk_fma_f32 v[84:85], v[46:47], v[136:137], v[84:85]
	v_pk_mul_f32 v[136:137], v[106:107], v[140:141] op_sel_hi:[0,1]
	v_pk_fma_f32 v[84:85], v[54:55], v[136:137], v[84:85]
	v_pk_mul_f32 v[118:119], v[108:109], v[118:119] op_sel_hi:[0,1]
	v_pk_fma_f32 v[84:85], v[62:63], v[118:119], v[84:85]
	v_lshlrev_b32_e32 v88, 16, v107
	v_and_b32_e32 v89, 0xffff0000, v107
	v_mul_f32_e32 v107, 0xbfb8aa3b, v84
	v_exp_f32_e32 v107, v107
	v_lshlrev_b32_e32 v110, 16, v111
	v_and_b32_e32 v111, 0xffff0000, v111
	v_lshlrev_b32_e32 v150, 16, v120
	v_add_f32_e32 v107, 1.0, v107
	v_rcp_f32_e32 v118, v107
	v_mul_f32_e32 v107, 0xbfb8aa3b, v85
	v_exp_f32_e32 v107, v107
	v_and_b32_e32 v151, 0xffff0000, v120
	v_lshlrev_b32_e32 v152, 16, v121
	v_and_b32_e32 v153, 0xffff0000, v121
	v_add_f32_e32 v107, 1.0, v107
	v_rcp_f32_e32 v119, v107
	v_lshlrev_b32_e32 v120, 16, v125
	v_and_b32_e32 v121, 0xffff0000, v125
	v_lshlrev_b32_e32 v138, 16, v112
	v_pk_mul_f32 v[84:85], v[84:85], v[118:119]
	v_and_b32_e32 v139, 0xffff0000, v112
	v_pk_mul_f32 v[84:85], v[84:85], s[60:61] op_sel_hi:[1,0]
	v_lshlrev_b32_e32 v124, 16, v126
	v_cvt_pk_bf16_f32 v118, v84, v85
	v_pk_mul_f32 v[84:85], v[0:1], v[88:89] op_sel_hi:[0,1]
	v_pk_fma_f32 v[84:85], v[44:45], v[84:85], v[32:33]
	v_pk_mul_f32 v[88:89], v[104:105], v[110:111] op_sel_hi:[0,1]
	v_pk_fma_f32 v[84:85], v[48:49], v[88:89], v[84:85]
	v_pk_mul_f32 v[88:89], v[106:107], v[142:143] op_sel_hi:[0,1]
	v_pk_fma_f32 v[84:85], v[56:57], v[88:89], v[84:85]
	v_pk_mul_f32 v[88:89], v[108:109], v[120:121] op_sel_hi:[0,1]
	v_pk_fma_f32 v[84:85], v[64:65], v[88:89], v[84:85]
	v_and_b32_e32 v125, 0xffff0000, v126
	v_mul_f32_e32 v88, 0xbfb8aa3b, v84
	v_mul_f32_e32 v89, 0xbfb8aa3b, v85
	v_exp_f32_e32 v88, v88
	v_exp_f32_e32 v89, v89
	v_lshlrev_b32_e32 v96, 16, v109
	v_and_b32_e32 v97, 0xffff0000, v109
	v_add_f32_e32 v88, 1.0, v88
	v_add_f32_e32 v89, 1.0, v89
	v_rcp_f32_e32 v88, v88
	v_rcp_f32_e32 v89, v89
	v_lshlrev_b32_e32 v112, 16, v113
	v_and_b32_e32 v113, 0xffff0000, v113
	v_lshlrev_b32_e32 v126, 16, v127
	v_pk_mul_f32 v[84:85], v[84:85], v[88:89]
	v_pk_mul_f32 v[88:89], v[104:105], v[138:139] op_sel_hi:[0,1]
	v_pk_mul_f32 v[84:85], v[84:85], s[60:61] op_sel_hi:[1,0]
	v_and_b32_e32 v127, 0xffff0000, v127
	v_cvt_pk_bf16_f32 v119, v84, v85
	v_pk_mul_f32 v[84:85], v[0:1], v[92:93] op_sel_hi:[0,1]
	v_pk_fma_f32 v[84:85], v[22:23], v[84:85], v[2:3]
	v_mad_u64_u32 v[110:111], s[40:41], v117, s28, v[98:99]
	v_pk_fma_f32 v[84:85], v[26:27], v[88:89], v[84:85]
	v_pk_mul_f32 v[88:89], v[106:107], v[150:151] op_sel_hi:[0,1]
	v_pk_fma_f32 v[84:85], v[38:39], v[88:89], v[84:85]
	v_pk_mul_f32 v[88:89], v[108:109], v[124:125] op_sel_hi:[0,1]
	v_pk_fma_f32 v[84:85], v[58:59], v[88:89], v[84:85]
	s_nop 0
	v_mul_f32_e32 v88, 0xbfb8aa3b, v84
	v_mul_f32_e32 v89, 0xbfb8aa3b, v85
	v_exp_f32_e32 v88, v88
	v_exp_f32_e32 v89, v89
	v_add_f32_e32 v88, 1.0, v88
	v_add_f32_e32 v89, 1.0, v89
	v_rcp_f32_e32 v88, v88
	v_rcp_f32_e32 v89, v89
	s_nop 0
	v_pk_mul_f32 v[84:85], v[84:85], v[88:89]
	s_nop 0
	v_pk_mul_f32 v[84:85], v[84:85], s[60:61] op_sel_hi:[1,0]
	v_pk_mul_f32 v[88:89], v[104:105], v[112:113] op_sel_hi:[0,1]
	v_cvt_pk_bf16_f32 v120, v84, v85
	v_pk_mul_f32 v[84:85], v[0:1], v[96:97] op_sel_hi:[0,1]
	v_pk_fma_f32 v[84:85], v[24:25], v[84:85], v[4:5]
	s_nop 0
	v_pk_fma_f32 v[84:85], v[28:29], v[88:89], v[84:85]
	v_pk_mul_f32 v[88:89], v[106:107], v[152:153] op_sel_hi:[0,1]
	v_pk_fma_f32 v[84:85], v[40:41], v[88:89], v[84:85]
	v_pk_mul_f32 v[88:89], v[108:109], v[126:127] op_sel_hi:[0,1]
	v_pk_fma_f32 v[84:85], v[60:61], v[88:89], v[84:85]
	s_nop 0
	v_mul_f32_e32 v88, 0xbfb8aa3b, v84
	v_mul_f32_e32 v89, 0xbfb8aa3b, v85
	v_exp_f32_e32 v88, v88
	v_exp_f32_e32 v89, v89
	v_add_f32_e32 v88, 1.0, v88
	v_add_f32_e32 v89, 1.0, v89
	v_rcp_f32_e32 v88, v88
	v_rcp_f32_e32 v89, v89
	s_nop 0
	v_pk_mul_f32 v[84:85], v[84:85], v[88:89]
	s_nop 0
	v_pk_mul_f32 v[84:85], v[84:85], s[60:61] op_sel_hi:[1,0]
	s_nop 0
	v_cvt_pk_bf16_f32 v121, v84, v85
	ds_write_b128 v110, v[118:121]
	global_load_dwordx4 v[82:85], v[82:83], off offset:1856
	s_nop 0
	global_load_dwordx4 v[86:89], v[86:87], off offset:1856
	s_nop 0
	global_load_dwordx4 v[90:93], v[90:91], off offset:1856
	s_nop 0
	global_load_dwordx4 v[94:97], v[94:95], off offset:1856
	s_waitcnt vmcnt(3)
	v_lshlrev_b32_e32 v112, 16, v82
	v_and_b32_e32 v113, 0xffff0000, v82
	s_waitcnt vmcnt(2)
	v_lshlrev_b32_e32 v120, 16, v86
	v_and_b32_e32 v121, 0xffff0000, v86
	v_pk_mul_f32 v[112:113], v[0:1], v[112:113] op_sel_hi:[0,1]
	s_waitcnt vmcnt(1)
	v_lshlrev_b32_e32 v126, 16, v90
	v_and_b32_e32 v127, 0xffff0000, v90
	v_pk_fma_f32 v[112:113], v[18:19], v[112:113], v[14:15]
	v_pk_mul_f32 v[120:121], v[104:105], v[120:121] op_sel_hi:[0,1]
	s_waitcnt vmcnt(0)
	v_lshlrev_b32_e32 v138, 16, v94
	v_and_b32_e32 v139, 0xffff0000, v94
	v_pk_fma_f32 v[112:113], v[50:51], v[120:121], v[112:113]
	v_pk_mul_f32 v[120:121], v[106:107], v[126:127] op_sel_hi:[0,1]
	v_pk_fma_f32 v[112:113], v[70:71], v[120:121], v[112:113]
	v_pk_mul_f32 v[120:121], v[108:109], v[138:139] op_sel_hi:[0,1]
	v_pk_fma_f32 v[112:113], v[74:75], v[120:121], v[112:113]
	v_lshlrev_b32_e32 v82, 16, v83
	v_mul_f32_e32 v107, 0xbfb8aa3b, v112
	v_exp_f32_e32 v107, v107
	v_and_b32_e32 v83, 0xffff0000, v83
	v_lshlrev_b32_e32 v86, 16, v87
	v_and_b32_e32 v87, 0xffff0000, v87
	v_add_f32_e32 v107, 1.0, v107
	v_rcp_f32_e32 v120, v107
	v_mul_f32_e32 v107, 0xbfb8aa3b, v113
	v_exp_f32_e32 v107, v107
	v_pk_mul_f32 v[82:83], v[0:1], v[82:83] op_sel_hi:[0,1]
	v_lshlrev_b32_e32 v90, 16, v91
	v_and_b32_e32 v91, 0xffff0000, v91
	v_add_f32_e32 v107, 1.0, v107
	v_pk_fma_f32 v[82:83], v[20:21], v[82:83], v[16:17]
	v_pk_mul_f32 v[86:87], v[104:105], v[86:87] op_sel_hi:[0,1]
	v_lshlrev_b32_e32 v94, 16, v95
	v_and_b32_e32 v95, 0xffff0000, v95
	v_pk_fma_f32 v[82:83], v[52:53], v[86:87], v[82:83]
	v_pk_mul_f32 v[86:87], v[106:107], v[90:91] op_sel_hi:[0,1]
	v_pk_fma_f32 v[82:83], v[72:73], v[86:87], v[82:83]
	v_pk_mul_f32 v[86:87], v[108:109], v[94:95] op_sel_hi:[0,1]
	v_pk_fma_f32 v[82:83], v[76:77], v[86:87], v[82:83]
	v_lshlrev_b32_e32 v118, 16, v84
	v_mul_f32_e32 v86, 0xbfb8aa3b, v82
	v_mul_f32_e32 v87, 0xbfb8aa3b, v83
	v_exp_f32_e32 v86, v86
	v_exp_f32_e32 v87, v87
	v_and_b32_e32 v119, 0xffff0000, v84
	v_lshlrev_b32_e32 v124, 16, v88
	v_add_f32_e32 v86, 1.0, v86
	v_add_f32_e32 v87, 1.0, v87
	v_rcp_f32_e32 v86, v86
	v_rcp_f32_e32 v87, v87
	v_and_b32_e32 v125, 0xffff0000, v88
	v_lshlrev_b32_e32 v136, 16, v92
	v_and_b32_e32 v137, 0xffff0000, v92
	v_pk_mul_f32 v[86:87], v[82:83], v[86:87]
	v_pk_mul_f32 v[82:83], v[0:1], v[118:119] op_sel_hi:[0,1]
	v_pk_fma_f32 v[82:83], v[10:11], v[82:83], v[6:7]
	v_pk_mul_f32 v[90:91], v[104:105], v[124:125] op_sel_hi:[0,1]
	v_lshlrev_b32_e32 v140, 16, v96
	v_and_b32_e32 v141, 0xffff0000, v96
	v_pk_fma_f32 v[82:83], v[34:35], v[90:91], v[82:83]
	v_pk_mul_f32 v[90:91], v[106:107], v[136:137] op_sel_hi:[0,1]
	v_pk_fma_f32 v[82:83], v[66:67], v[90:91], v[82:83]
	v_pk_mul_f32 v[90:91], v[108:109], v[140:141] op_sel_hi:[0,1]
	v_pk_fma_f32 v[82:83], v[78:79], v[90:91], v[82:83]
	v_lshlrev_b32_e32 v84, 16, v85
	v_mul_f32_e32 v90, 0xbfb8aa3b, v82
	v_mul_f32_e32 v91, 0xbfb8aa3b, v83
	v_exp_f32_e32 v90, v90
	v_exp_f32_e32 v91, v91
	v_and_b32_e32 v85, 0xffff0000, v85
	v_lshlrev_b32_e32 v88, 16, v89
	v_add_f32_e32 v90, 1.0, v90
	v_add_f32_e32 v91, 1.0, v91
	v_rcp_f32_e32 v90, v90
	v_rcp_f32_e32 v91, v91
	v_and_b32_e32 v89, 0xffff0000, v89
	v_lshlrev_b32_e32 v92, 16, v93
	v_and_b32_e32 v93, 0xffff0000, v93
	v_pk_mul_f32 v[90:91], v[82:83], v[90:91]
	v_pk_mul_f32 v[82:83], v[0:1], v[84:85] op_sel_hi:[0,1]
	v_pk_fma_f32 v[82:83], v[12:13], v[82:83], v[8:9]
	v_pk_mul_f32 v[84:85], v[104:105], v[88:89] op_sel_hi:[0,1]
	v_lshlrev_b32_e32 v96, 16, v97
	v_and_b32_e32 v97, 0xffff0000, v97
	v_pk_fma_f32 v[82:83], v[36:37], v[84:85], v[82:83]
	v_pk_mul_f32 v[84:85], v[106:107], v[92:93] op_sel_hi:[0,1]
	v_pk_fma_f32 v[82:83], v[68:69], v[84:85], v[82:83]
	v_pk_mul_f32 v[84:85], v[108:109], v[96:97] op_sel_hi:[0,1]
	v_pk_fma_f32 v[82:83], v[80:81], v[84:85], v[82:83]
	v_rcp_f32_e32 v121, v107
	v_mul_f32_e32 v0, 0xbfb8aa3b, v82
	v_exp_f32_e32 v0, v0
	v_lshlrev_b32_e32 v118, 7, v117
	v_pk_mul_f32 v[112:113], v[112:113], v[120:121]
	v_ashrrev_i32_e32 v119, 31, v118
	v_add_f32_e32 v0, 1.0, v0
	v_rcp_f32_e32 v84, v0
	v_mul_f32_e32 v0, 0xbfb8aa3b, v83
	v_exp_f32_e32 v0, v0
	s_nop 0
	v_add_f32_e32 v0, 1.0, v0
	v_rcp_f32_e32 v85, v0
	v_lshlrev_b32_e32 v0, 5, v117
	v_bitop3_b32 v123, v0, v135, s95 bitop3:0x6c
	v_pk_mul_f32 v[88:89], v[82:83], v[84:85]
	v_cvt_pk_bf16_f32 v82, v112, v113
	v_cvt_pk_bf16_f32 v83, v86, v87
	v_cvt_pk_bf16_f32 v84, v90, v91
	v_cvt_pk_bf16_f32 v85, v88, v89
	ds_write_b128 v110, v[82:85] offset:17408
	v_mad_i64_i32 v[82:83], s[40:41], v105, s89, v[100:101]
	v_lshl_add_u64 v[82:83], v[82:83], 0, s[16:17]
	v_lshl_add_u64 v[82:83], v[82:83], 0, v[98:99]
	v_and_b32_e32 v84, 0x60, v0
	v_bitop3_b32 v0, v84, v118, v135 bitop3:0xde
	global_load_dwordx4 v[82:85], v[82:83], off offset:2880
	v_lshlrev_b32_e32 v0, 1, v0
	s_waitcnt vmcnt(0)
	ds_write_b128 v0, v[82:85] offset:34816
	v_lshl_add_u64 v[82:83], v[118:119], 1, v[114:115]
	global_load_dwordx4 v[82:85], v[82:83], off
	s_waitcnt vmcnt(0)
	ds_write_b128 v0, v[82:85] offset:51200
	v_add_u32_e32 v0, 0x200, v129
	v_ashrrev_i32_e32 v119, 4, v0
	v_add_u32_e32 v105, s92, v119
	v_max_i32_e32 v0, 3, v105
	v_add_u32_e32 v0, -3, v0
	v_mad_u64_u32 v[82:83], s[40:41], v0, s89, v[100:101]
	v_max_i32_e32 v0, 2, v105
	v_add_u32_e32 v0, -2, v0
	v_mad_u64_u32 v[84:85], s[40:41], v0, s89, v[100:101]
	v_max_i32_e32 v0, 1, v105
	v_lshl_add_u64 v[82:83], v[82:83], 0, v[102:103]
	v_add_u32_e32 v0, -1, v0
	global_load_dwordx4 v[106:109], v[82:83], off offset:832
	v_lshl_add_u64 v[86:87], v[84:85], 0, v[102:103]
	v_mad_u64_u32 v[84:85], s[40:41], v0, s89, v[100:101]
	v_max_i32_e32 v0, 0, v105
	global_load_dwordx4 v[110:113], v[86:87], off offset:832
	v_lshl_add_u64 v[90:91], v[84:85], 0, v[102:103]
	v_mad_u64_u32 v[84:85], s[40:41], v0, s89, v[100:101]
	global_load_dwordx4 v[124:127], v[90:91], off offset:832
	v_lshl_add_u64 v[94:95], v[84:85], 0, v[102:103]
	global_load_dwordx4 v[136:139], v[94:95], off offset:832
	v_cmp_lt_i32_e32 vcc, 2, v105
	s_waitcnt vmcnt(3)
	v_lshlrev_b32_e32 v84, 16, v106
	v_cndmask_b32_e64 v0, 0, 1.0, vcc
	v_and_b32_e32 v85, 0xffff0000, v106
	v_cmp_lt_i32_e32 vcc, 1, v105
	v_pk_mul_f32 v[84:85], v[0:1], v[84:85] op_sel_hi:[0,1]
	s_waitcnt vmcnt(2)
	v_lshlrev_b32_e32 v120, 16, v110
	v_cndmask_b32_e64 v104, 0, 1.0, vcc
	v_and_b32_e32 v121, 0xffff0000, v110
	v_cmp_lt_i32_e32 vcc, 0, v105
	s_waitcnt vmcnt(1)
	v_lshlrev_b32_e32 v142, 16, v124
	v_and_b32_e32 v143, 0xffff0000, v124
	v_cndmask_b32_e64 v106, 0, 1.0, vcc
	v_cmp_lt_i32_e32 vcc, -1, v105
	v_pk_fma_f32 v[84:85], v[42:43], v[84:85], v[30:31]
	v_pk_mul_f32 v[120:121], v[104:105], v[120:121] op_sel_hi:[0,1]
	v_lshlrev_b32_e32 v92, 16, v108
	v_and_b32_e32 v93, 0xffff0000, v108
	v_lshlrev_b32_e32 v150, 16, v125
	v_and_b32_e32 v151, 0xffff0000, v125
	v_cndmask_b32_e64 v108, 0, 1.0, vcc
	s_waitcnt vmcnt(0)
	v_lshlrev_b32_e32 v124, 16, v136
	v_and_b32_e32 v125, 0xffff0000, v136
	v_pk_fma_f32 v[84:85], v[46:47], v[120:121], v[84:85]
	v_pk_mul_f32 v[120:121], v[106:107], v[142:143] op_sel_hi:[0,1]
	v_pk_fma_f32 v[84:85], v[54:55], v[120:121], v[84:85]
	v_pk_mul_f32 v[120:121], v[108:109], v[124:125] op_sel_hi:[0,1]
	v_pk_fma_f32 v[84:85], v[62:63], v[120:121], v[84:85]
	v_lshlrev_b32_e32 v88, 16, v107
	v_and_b32_e32 v89, 0xffff0000, v107
	v_mul_f32_e32 v107, 0xbfb8aa3b, v84
	v_exp_f32_e32 v107, v107
	v_lshlrev_b32_e32 v110, 16, v111
	v_and_b32_e32 v111, 0xffff0000, v111
	v_lshlrev_b32_e32 v152, 16, v126
	v_add_f32_e32 v107, 1.0, v107
	v_rcp_f32_e32 v120, v107
	v_mul_f32_e32 v107, 0xbfb8aa3b, v85
	v_exp_f32_e32 v107, v107
	v_and_b32_e32 v153, 0xffff0000, v126
	v_lshlrev_b32_e32 v154, 16, v127
	v_and_b32_e32 v155, 0xffff0000, v127
	v_add_f32_e32 v107, 1.0, v107
	v_rcp_f32_e32 v121, v107
	v_lshlrev_b32_e32 v126, 16, v137
	v_and_b32_e32 v127, 0xffff0000, v137
	v_lshlrev_b32_e32 v140, 16, v112
	v_pk_mul_f32 v[84:85], v[84:85], v[120:121]
	v_and_b32_e32 v141, 0xffff0000, v112
	v_pk_mul_f32 v[84:85], v[84:85], s[60:61] op_sel_hi:[1,0]
	v_lshlrev_b32_e32 v136, 16, v138
	v_cvt_pk_bf16_f32 v124, v84, v85
	v_pk_mul_f32 v[84:85], v[0:1], v[88:89] op_sel_hi:[0,1]
	v_pk_fma_f32 v[84:85], v[44:45], v[84:85], v[32:33]
	v_pk_mul_f32 v[88:89], v[104:105], v[110:111] op_sel_hi:[0,1]
	v_pk_fma_f32 v[84:85], v[48:49], v[88:89], v[84:85]
	v_pk_mul_f32 v[88:89], v[106:107], v[150:151] op_sel_hi:[0,1]
	v_pk_fma_f32 v[84:85], v[56:57], v[88:89], v[84:85]
	v_pk_mul_f32 v[88:89], v[108:109], v[126:127] op_sel_hi:[0,1]
	v_pk_fma_f32 v[84:85], v[64:65], v[88:89], v[84:85]
	v_and_b32_e32 v137, 0xffff0000, v138
	v_mul_f32_e32 v88, 0xbfb8aa3b, v84
	v_mul_f32_e32 v89, 0xbfb8aa3b, v85
	v_exp_f32_e32 v88, v88
	v_exp_f32_e32 v89, v89
	v_lshlrev_b32_e32 v96, 16, v109
	v_and_b32_e32 v97, 0xffff0000, v109
	v_add_f32_e32 v88, 1.0, v88
	v_add_f32_e32 v89, 1.0, v89
	v_rcp_f32_e32 v88, v88
	v_rcp_f32_e32 v89, v89
	v_lshlrev_b32_e32 v112, 16, v113
	v_and_b32_e32 v113, 0xffff0000, v113
	v_lshlrev_b32_e32 v138, 16, v139
	v_pk_mul_f32 v[84:85], v[84:85], v[88:89]
	v_pk_mul_f32 v[88:89], v[104:105], v[140:141] op_sel_hi:[0,1]
	v_pk_mul_f32 v[84:85], v[84:85], s[60:61] op_sel_hi:[1,0]
	v_and_b32_e32 v139, 0xffff0000, v139
	v_cvt_pk_bf16_f32 v125, v84, v85
	v_pk_mul_f32 v[84:85], v[0:1], v[92:93] op_sel_hi:[0,1]
	v_pk_fma_f32 v[84:85], v[22:23], v[84:85], v[2:3]
	v_mad_u64_u32 v[110:111], s[40:41], v119, s28, v[98:99]
	v_pk_fma_f32 v[84:85], v[26:27], v[88:89], v[84:85]
	v_pk_mul_f32 v[88:89], v[106:107], v[152:153] op_sel_hi:[0,1]
	v_pk_fma_f32 v[84:85], v[38:39], v[88:89], v[84:85]
	v_pk_mul_f32 v[88:89], v[108:109], v[136:137] op_sel_hi:[0,1]
	v_pk_fma_f32 v[84:85], v[58:59], v[88:89], v[84:85]
	s_nop 0
	v_mul_f32_e32 v88, 0xbfb8aa3b, v84
	v_mul_f32_e32 v89, 0xbfb8aa3b, v85
	v_exp_f32_e32 v88, v88
	v_exp_f32_e32 v89, v89
	v_add_f32_e32 v88, 1.0, v88
	v_add_f32_e32 v89, 1.0, v89
	v_rcp_f32_e32 v88, v88
	v_rcp_f32_e32 v89, v89
	s_nop 0
	v_pk_mul_f32 v[84:85], v[84:85], v[88:89]
	s_nop 0
	v_pk_mul_f32 v[84:85], v[84:85], s[60:61] op_sel_hi:[1,0]
	v_pk_mul_f32 v[88:89], v[104:105], v[112:113] op_sel_hi:[0,1]
	v_cvt_pk_bf16_f32 v126, v84, v85
	v_pk_mul_f32 v[84:85], v[0:1], v[96:97] op_sel_hi:[0,1]
	v_pk_fma_f32 v[84:85], v[24:25], v[84:85], v[4:5]
	s_nop 0
	v_pk_fma_f32 v[84:85], v[28:29], v[88:89], v[84:85]
	v_pk_mul_f32 v[88:89], v[106:107], v[154:155] op_sel_hi:[0,1]
	v_pk_fma_f32 v[84:85], v[40:41], v[88:89], v[84:85]
	v_pk_mul_f32 v[88:89], v[108:109], v[138:139] op_sel_hi:[0,1]
	v_pk_fma_f32 v[84:85], v[60:61], v[88:89], v[84:85]
	s_nop 0
	v_mul_f32_e32 v88, 0xbfb8aa3b, v84
	v_mul_f32_e32 v89, 0xbfb8aa3b, v85
	v_exp_f32_e32 v88, v88
	v_exp_f32_e32 v89, v89
	v_add_f32_e32 v88, 1.0, v88
	v_add_f32_e32 v89, 1.0, v89
	v_rcp_f32_e32 v88, v88
	v_rcp_f32_e32 v89, v89
	s_nop 0
	v_pk_mul_f32 v[84:85], v[84:85], v[88:89]
	s_nop 0
	v_pk_mul_f32 v[84:85], v[84:85], s[60:61] op_sel_hi:[1,0]
	s_nop 0
	v_cvt_pk_bf16_f32 v127, v84, v85
	ds_write_b128 v110, v[124:127]
	global_load_dwordx4 v[82:85], v[82:83], off offset:1856
	s_nop 0
	global_load_dwordx4 v[86:89], v[86:87], off offset:1856
	s_nop 0
	global_load_dwordx4 v[90:93], v[90:91], off offset:1856
	s_nop 0
	global_load_dwordx4 v[94:97], v[94:95], off offset:1856
	s_waitcnt vmcnt(3)
	v_lshlrev_b32_e32 v112, 16, v82
	v_and_b32_e32 v113, 0xffff0000, v82
	s_waitcnt vmcnt(2)
	v_lshlrev_b32_e32 v124, 16, v86
	v_and_b32_e32 v125, 0xffff0000, v86
	v_pk_mul_f32 v[112:113], v[0:1], v[112:113] op_sel_hi:[0,1]
	s_waitcnt vmcnt(1)
	v_lshlrev_b32_e32 v136, 16, v90
	v_and_b32_e32 v137, 0xffff0000, v90
	v_pk_fma_f32 v[112:113], v[18:19], v[112:113], v[14:15]
	v_pk_mul_f32 v[124:125], v[104:105], v[124:125] op_sel_hi:[0,1]
	s_waitcnt vmcnt(0)
	v_lshlrev_b32_e32 v140, 16, v94
	v_and_b32_e32 v141, 0xffff0000, v94
	v_pk_fma_f32 v[112:113], v[50:51], v[124:125], v[112:113]
	v_pk_mul_f32 v[124:125], v[106:107], v[136:137] op_sel_hi:[0,1]
	v_pk_fma_f32 v[112:113], v[70:71], v[124:125], v[112:113]
	v_pk_mul_f32 v[124:125], v[108:109], v[140:141] op_sel_hi:[0,1]
	v_pk_fma_f32 v[112:113], v[74:75], v[124:125], v[112:113]
	v_lshlrev_b32_e32 v82, 16, v83
	v_mul_f32_e32 v107, 0xbfb8aa3b, v112
	v_exp_f32_e32 v107, v107
	v_and_b32_e32 v83, 0xffff0000, v83
	v_lshlrev_b32_e32 v86, 16, v87
	v_and_b32_e32 v87, 0xffff0000, v87
	v_add_f32_e32 v107, 1.0, v107
	v_rcp_f32_e32 v124, v107
	v_mul_f32_e32 v107, 0xbfb8aa3b, v113
	v_exp_f32_e32 v107, v107
	v_pk_mul_f32 v[82:83], v[0:1], v[82:83] op_sel_hi:[0,1]
	v_lshlrev_b32_e32 v90, 16, v91
	v_and_b32_e32 v91, 0xffff0000, v91
	v_add_f32_e32 v107, 1.0, v107
	v_pk_fma_f32 v[82:83], v[20:21], v[82:83], v[16:17]
	v_pk_mul_f32 v[86:87], v[104:105], v[86:87] op_sel_hi:[0,1]
	v_lshlrev_b32_e32 v94, 16, v95
	v_and_b32_e32 v95, 0xffff0000, v95
	v_pk_fma_f32 v[82:83], v[52:53], v[86:87], v[82:83]
	v_pk_mul_f32 v[86:87], v[106:107], v[90:91] op_sel_hi:[0,1]
	v_pk_fma_f32 v[82:83], v[72:73], v[86:87], v[82:83]
	v_pk_mul_f32 v[86:87], v[108:109], v[94:95] op_sel_hi:[0,1]
	v_pk_fma_f32 v[82:83], v[76:77], v[86:87], v[82:83]
	v_lshlrev_b32_e32 v120, 16, v84
	v_mul_f32_e32 v86, 0xbfb8aa3b, v82
	v_mul_f32_e32 v87, 0xbfb8aa3b, v83
	v_exp_f32_e32 v86, v86
	v_exp_f32_e32 v87, v87
	v_and_b32_e32 v121, 0xffff0000, v84
	v_lshlrev_b32_e32 v126, 16, v88
	v_add_f32_e32 v86, 1.0, v86
	v_add_f32_e32 v87, 1.0, v87
	v_rcp_f32_e32 v86, v86
	v_rcp_f32_e32 v87, v87
	v_and_b32_e32 v127, 0xffff0000, v88
	v_lshlrev_b32_e32 v138, 16, v92
	v_and_b32_e32 v139, 0xffff0000, v92
	v_pk_mul_f32 v[86:87], v[82:83], v[86:87]
	v_pk_mul_f32 v[82:83], v[0:1], v[120:121] op_sel_hi:[0,1]
	v_pk_fma_f32 v[82:83], v[10:11], v[82:83], v[6:7]
	v_pk_mul_f32 v[90:91], v[104:105], v[126:127] op_sel_hi:[0,1]
	v_lshlrev_b32_e32 v142, 16, v96
	v_and_b32_e32 v143, 0xffff0000, v96
	v_pk_fma_f32 v[82:83], v[34:35], v[90:91], v[82:83]
	v_pk_mul_f32 v[90:91], v[106:107], v[138:139] op_sel_hi:[0,1]
	v_pk_fma_f32 v[82:83], v[66:67], v[90:91], v[82:83]
	v_pk_mul_f32 v[90:91], v[108:109], v[142:143] op_sel_hi:[0,1]
	v_pk_fma_f32 v[82:83], v[78:79], v[90:91], v[82:83]
	v_lshlrev_b32_e32 v84, 16, v85
	v_mul_f32_e32 v90, 0xbfb8aa3b, v82
	v_mul_f32_e32 v91, 0xbfb8aa3b, v83
	v_exp_f32_e32 v90, v90
	v_exp_f32_e32 v91, v91
	v_and_b32_e32 v85, 0xffff0000, v85
	v_lshlrev_b32_e32 v88, 16, v89
	v_add_f32_e32 v90, 1.0, v90
	v_add_f32_e32 v91, 1.0, v91
	v_rcp_f32_e32 v90, v90
	v_rcp_f32_e32 v91, v91
	v_and_b32_e32 v89, 0xffff0000, v89
	v_lshlrev_b32_e32 v92, 16, v93
	v_and_b32_e32 v93, 0xffff0000, v93
	v_pk_mul_f32 v[90:91], v[82:83], v[90:91]
	v_pk_mul_f32 v[82:83], v[0:1], v[84:85] op_sel_hi:[0,1]
	v_pk_fma_f32 v[82:83], v[12:13], v[82:83], v[8:9]
	v_pk_mul_f32 v[84:85], v[104:105], v[88:89] op_sel_hi:[0,1]
	v_lshlrev_b32_e32 v96, 16, v97
	v_and_b32_e32 v97, 0xffff0000, v97
	v_pk_fma_f32 v[82:83], v[36:37], v[84:85], v[82:83]
	v_pk_mul_f32 v[84:85], v[106:107], v[92:93] op_sel_hi:[0,1]
	v_pk_fma_f32 v[82:83], v[68:69], v[84:85], v[82:83]
	v_pk_mul_f32 v[84:85], v[108:109], v[96:97] op_sel_hi:[0,1]
	v_pk_fma_f32 v[82:83], v[80:81], v[84:85], v[82:83]
	v_rcp_f32_e32 v125, v107
	v_mul_f32_e32 v0, 0xbfb8aa3b, v82
	v_exp_f32_e32 v0, v0
	v_lshlrev_b32_e32 v120, 7, v119
	v_pk_mul_f32 v[112:113], v[112:113], v[124:125]
	v_ashrrev_i32_e32 v121, 31, v120
	v_add_f32_e32 v0, 1.0, v0
	v_rcp_f32_e32 v84, v0
	v_mul_f32_e32 v0, 0xbfb8aa3b, v83
	v_exp_f32_e32 v0, v0
	s_nop 0
	v_add_f32_e32 v0, 1.0, v0
	v_rcp_f32_e32 v85, v0
	v_lshlrev_b32_e32 v0, 5, v119
	v_bitop3_b32 v124, v0, v135, s95 bitop3:0x6c
	v_pk_mul_f32 v[88:89], v[82:83], v[84:85]
	v_cvt_pk_bf16_f32 v82, v112, v113
	v_cvt_pk_bf16_f32 v83, v86, v87
	v_cvt_pk_bf16_f32 v84, v90, v91
	v_cvt_pk_bf16_f32 v85, v88, v89
	ds_write_b128 v110, v[82:85] offset:17408
	v_mad_i64_i32 v[82:83], s[40:41], v105, s89, v[100:101]
	v_lshl_add_u64 v[82:83], v[82:83], 0, s[16:17]
	v_lshl_add_u64 v[82:83], v[82:83], 0, v[98:99]
	v_and_b32_e32 v84, 0x60, v0
	v_bitop3_b32 v0, v84, v120, v135 bitop3:0xde
	global_load_dwordx4 v[82:85], v[82:83], off offset:2880
	v_lshlrev_b32_e32 v0, 1, v0
	s_waitcnt vmcnt(0)
	ds_write_b128 v0, v[82:85] offset:34816
	v_lshl_add_u64 v[82:83], v[120:121], 1, v[114:115]
	global_load_dwordx4 v[82:85], v[82:83], off
	v_and_or_b32 v121, s0, 32, v133
	s_waitcnt vmcnt(0)
	ds_write_b128 v0, v[82:85] offset:51200
	v_add_u32_e32 v0, 0x300, v129
	v_ashrrev_i32_e32 v126, 4, v0
	v_add_u32_e32 v83, s92, v126
	v_max_i32_e32 v0, 3, v83
	v_add_u32_e32 v0, -3, v0
	v_mad_u64_u32 v[84:85], s[40:41], v0, s89, v[100:101]
	v_max_i32_e32 v0, 2, v83
	v_add_u32_e32 v0, -2, v0
	v_mad_u64_u32 v[88:89], s[40:41], v0, s89, v[100:101]
	v_max_i32_e32 v0, 1, v83
	v_lshl_add_u64 v[94:95], v[84:85], 0, v[102:103]
	v_add_u32_e32 v0, -1, v0
	global_load_dwordx4 v[84:87], v[94:95], off offset:832
	v_lshl_add_u64 v[92:93], v[88:89], 0, v[102:103]
	v_mad_u64_u32 v[88:89], s[40:41], v0, s89, v[100:101]
	v_max_i32_e32 v0, 0, v83
	global_load_dwordx4 v[104:107], v[92:93], off offset:832
	v_lshl_add_u64 v[90:91], v[88:89], 0, v[102:103]
	v_mad_u64_u32 v[88:89], s[40:41], v0, s89, v[100:101]
	global_load_dwordx4 v[108:111], v[90:91], off offset:832
	v_lshl_add_u64 v[88:89], v[88:89], 0, v[102:103]
	global_load_dwordx4 v[136:139], v[88:89], off offset:832
	v_cmp_lt_i32_e32 vcc, 2, v83
	s_waitcnt vmcnt(3)
	v_lshlrev_b32_e32 v96, 16, v84
	v_cndmask_b32_e64 v0, 0, 1.0, vcc
	v_and_b32_e32 v97, 0xffff0000, v84
	v_cmp_lt_i32_e32 vcc, 1, v83
	v_pk_mul_f32 v[96:97], v[0:1], v[96:97] op_sel_hi:[0,1]
	s_waitcnt vmcnt(2)
	v_lshlrev_b32_e32 v142, 16, v104
	v_cndmask_b32_e64 v82, 0, 1.0, vcc
	v_and_b32_e32 v143, 0xffff0000, v104
	v_cmp_lt_i32_e32 vcc, 0, v83
	s_waitcnt vmcnt(1)
	v_lshlrev_b32_e32 v152, 16, v108
	v_and_b32_e32 v153, 0xffff0000, v108
	v_cndmask_b32_e64 v84, 0, 1.0, vcc
	v_cmp_lt_i32_e32 vcc, -1, v83
	v_pk_fma_f32 v[30:31], v[42:43], v[96:97], v[30:31]
	v_pk_mul_f32 v[42:43], v[82:83], v[142:143] op_sel_hi:[0,1]
	v_lshlrev_b32_e32 v112, 16, v86
	v_and_b32_e32 v113, 0xffff0000, v86
	v_cndmask_b32_e64 v86, 0, 1.0, vcc
	s_waitcnt vmcnt(0)
	v_lshlrev_b32_e32 v156, 16, v136
	v_and_b32_e32 v157, 0xffff0000, v136
	v_pk_fma_f32 v[30:31], v[46:47], v[42:43], v[30:31]
	v_pk_mul_f32 v[42:43], v[84:85], v[152:153] op_sel_hi:[0,1]
	v_pk_fma_f32 v[30:31], v[54:55], v[42:43], v[30:31]
	v_pk_mul_f32 v[42:43], v[86:87], v[156:157] op_sel_hi:[0,1]
	v_pk_fma_f32 v[30:31], v[62:63], v[42:43], v[30:31]
	v_lshlrev_b32_e32 v102, 16, v85
	v_mul_f32_e32 v42, 0xbfb8aa3b, v30
	v_mul_f32_e32 v43, 0xbfb8aa3b, v31
	v_exp_f32_e32 v42, v42
	v_exp_f32_e32 v43, v43
	v_and_b32_e32 v103, 0xffff0000, v85
	v_lshlrev_b32_e32 v104, 16, v105
	v_add_f32_e32 v42, 1.0, v42
	v_add_f32_e32 v43, 1.0, v43
	v_rcp_f32_e32 v42, v42
	v_rcp_f32_e32 v43, v43
	v_and_b32_e32 v105, 0xffff0000, v105
	v_lshlrev_b32_e32 v108, 16, v109
	v_and_b32_e32 v109, 0xffff0000, v109
	v_pk_mul_f32 v[30:31], v[30:31], v[42:43]
	v_pk_mul_f32 v[42:43], v[0:1], v[102:103] op_sel_hi:[0,1]
	v_pk_fma_f32 v[32:33], v[44:45], v[42:43], v[32:33]
	v_pk_mul_f32 v[42:43], v[82:83], v[104:105] op_sel_hi:[0,1]
	v_lshlrev_b32_e32 v136, 16, v137
	v_and_b32_e32 v137, 0xffff0000, v137
	v_pk_fma_f32 v[32:33], v[48:49], v[42:43], v[32:33]
	v_pk_mul_f32 v[42:43], v[84:85], v[108:109] op_sel_hi:[0,1]
	v_pk_fma_f32 v[32:33], v[56:57], v[42:43], v[32:33]
	v_pk_mul_f32 v[42:43], v[86:87], v[136:137] op_sel_hi:[0,1]
	v_pk_mul_f32 v[30:31], v[30:31], s[60:61] op_sel_hi:[1,0]
	v_pk_fma_f32 v[32:33], v[64:65], v[42:43], v[32:33]
	v_cvt_pk_bf16_f32 v30, v30, v31
	v_mul_f32_e32 v31, 0xbfb8aa3b, v32
	v_exp_f32_e32 v31, v31
	v_lshlrev_b32_e32 v150, 16, v106
	v_and_b32_e32 v151, 0xffff0000, v106
	v_lshlrev_b32_e32 v154, 16, v110
	v_add_f32_e32 v31, 1.0, v31
	v_rcp_f32_e32 v42, v31
	v_mul_f32_e32 v31, 0xbfb8aa3b, v33
	v_exp_f32_e32 v31, v31
	v_and_b32_e32 v155, 0xffff0000, v110
	v_lshlrev_b32_e32 v158, 16, v138
	v_and_b32_e32 v159, 0xffff0000, v138
	v_add_f32_e32 v31, 1.0, v31
	v_rcp_f32_e32 v43, v31
	v_lshlrev_b32_e32 v140, 16, v87
	v_and_b32_e32 v141, 0xffff0000, v87
	v_lshlrev_b32_e32 v106, 16, v107
	v_pk_mul_f32 v[32:33], v[32:33], v[42:43]
	v_and_b32_e32 v107, 0xffff0000, v107
	v_pk_mul_f32 v[32:33], v[32:33], s[60:61] op_sel_hi:[1,0]
	v_lshlrev_b32_e32 v110, 16, v111
	v_cvt_pk_bf16_f32 v31, v32, v33
	v_pk_mul_f32 v[32:33], v[0:1], v[112:113] op_sel_hi:[0,1]
	v_pk_fma_f32 v[2:3], v[22:23], v[32:33], v[2:3]
	v_pk_mul_f32 v[22:23], v[82:83], v[150:151] op_sel_hi:[0,1]
	v_pk_fma_f32 v[2:3], v[26:27], v[22:23], v[2:3]
	v_pk_mul_f32 v[22:23], v[84:85], v[154:155] op_sel_hi:[0,1]
	v_pk_fma_f32 v[2:3], v[38:39], v[22:23], v[2:3]
	v_pk_mul_f32 v[22:23], v[86:87], v[158:159] op_sel_hi:[0,1]
	v_pk_fma_f32 v[2:3], v[58:59], v[22:23], v[2:3]
	v_and_b32_e32 v111, 0xffff0000, v111
	v_mul_f32_e32 v22, 0xbfb8aa3b, v2
	v_mul_f32_e32 v23, 0xbfb8aa3b, v3
	v_exp_f32_e32 v22, v22
	v_exp_f32_e32 v23, v23
	v_lshlrev_b32_e32 v138, 16, v139
	v_and_b32_e32 v139, 0xffff0000, v139
	v_add_f32_e32 v22, 1.0, v22
	v_add_f32_e32 v23, 1.0, v23
	v_rcp_f32_e32 v22, v22
	v_rcp_f32_e32 v23, v23
	v_mad_u64_u32 v[38:39], s[40:41], v126, s28, v[98:99]
	v_pk_mul_f32 v[2:3], v[2:3], v[22:23]
	s_nop 0
	v_pk_mul_f32 v[2:3], v[2:3], s[60:61] op_sel_hi:[1,0]
	s_nop 0
	v_cvt_pk_bf16_f32 v32, v2, v3
	v_pk_mul_f32 v[2:3], v[0:1], v[140:141] op_sel_hi:[0,1]
	v_pk_fma_f32 v[2:3], v[24:25], v[2:3], v[4:5]
	v_pk_mul_f32 v[4:5], v[82:83], v[106:107] op_sel_hi:[0,1]
	v_pk_fma_f32 v[2:3], v[28:29], v[4:5], v[2:3]
	v_pk_mul_f32 v[4:5], v[84:85], v[110:111] op_sel_hi:[0,1]
	v_pk_fma_f32 v[2:3], v[40:41], v[4:5], v[2:3]
	v_pk_mul_f32 v[4:5], v[86:87], v[138:139] op_sel_hi:[0,1]
	v_pk_fma_f32 v[2:3], v[60:61], v[4:5], v[2:3]
	s_nop 0
	v_mul_f32_e32 v4, 0xbfb8aa3b, v2
	v_mul_f32_e32 v5, 0xbfb8aa3b, v3
	v_exp_f32_e32 v4, v4
	v_exp_f32_e32 v5, v5
	v_add_f32_e32 v4, 1.0, v4
	v_add_f32_e32 v5, 1.0, v5
	v_rcp_f32_e32 v4, v4
	v_rcp_f32_e32 v5, v5
	s_nop 0
	v_pk_mul_f32 v[2:3], v[2:3], v[4:5]
	s_nop 0
	v_pk_mul_f32 v[2:3], v[2:3], s[60:61] op_sel_hi:[1,0]
	s_nop 0
	v_cvt_pk_bf16_f32 v33, v2, v3
	ds_write_b128 v38, v[30:33]
	global_load_dwordx4 v[2:5], v[94:95], off offset:1856
	global_load_dwordx4 v[22:25], v[92:93], off offset:1856
	global_load_dwordx4 v[26:29], v[90:91], off offset:1856
	global_load_dwordx4 v[30:33], v[88:89], off offset:1856
	s_waitcnt vmcnt(3)
	v_lshlrev_b32_e32 v40, 16, v2
	v_and_b32_e32 v41, 0xffff0000, v2
	v_lshlrev_b32_e32 v2, 16, v3
	v_and_b32_e32 v3, 0xffff0000, v3
	s_waitcnt vmcnt(2)
	v_lshlrev_b32_e32 v44, 16, v22
	v_and_b32_e32 v45, 0xffff0000, v22
	v_lshlrev_b32_e32 v22, 16, v23
	v_and_b32_e32 v23, 0xffff0000, v23
	v_pk_mul_f32 v[2:3], v[0:1], v[2:3] op_sel_hi:[0,1]
	s_waitcnt vmcnt(1)
	v_lshlrev_b32_e32 v48, 16, v26
	v_and_b32_e32 v49, 0xffff0000, v26
	v_lshlrev_b32_e32 v26, 16, v27
	v_and_b32_e32 v27, 0xffff0000, v27
	v_pk_fma_f32 v[2:3], v[20:21], v[2:3], v[16:17]
	v_pk_mul_f32 v[16:17], v[82:83], v[22:23] op_sel_hi:[0,1]
	s_waitcnt vmcnt(0)
	v_lshlrev_b32_e32 v56, 16, v30
	v_and_b32_e32 v57, 0xffff0000, v30
	v_lshlrev_b32_e32 v30, 16, v31
	v_and_b32_e32 v31, 0xffff0000, v31
	v_pk_fma_f32 v[2:3], v[52:53], v[16:17], v[2:3]
	v_pk_mul_f32 v[16:17], v[84:85], v[26:27] op_sel_hi:[0,1]
	v_pk_fma_f32 v[2:3], v[72:73], v[16:17], v[2:3]
	v_pk_mul_f32 v[16:17], v[86:87], v[30:31] op_sel_hi:[0,1]
	v_pk_fma_f32 v[2:3], v[76:77], v[16:17], v[2:3]
	v_lshlrev_b32_e32 v42, 16, v4
	v_mul_f32_e32 v16, 0xbfb8aa3b, v2
	v_mul_f32_e32 v17, 0xbfb8aa3b, v3
	v_exp_f32_e32 v16, v16
	v_exp_f32_e32 v17, v17
	v_and_b32_e32 v43, 0xffff0000, v4
	v_lshlrev_b32_e32 v46, 16, v24
	v_add_f32_e32 v16, 1.0, v16
	v_add_f32_e32 v17, 1.0, v17
	v_rcp_f32_e32 v16, v16
	v_rcp_f32_e32 v17, v17
	v_and_b32_e32 v47, 0xffff0000, v24
	v_lshlrev_b32_e32 v54, 16, v28
	v_and_b32_e32 v55, 0xffff0000, v28
	v_pk_mul_f32 v[16:17], v[2:3], v[16:17]
	v_pk_mul_f32 v[2:3], v[0:1], v[42:43] op_sel_hi:[0,1]
	v_pk_fma_f32 v[2:3], v[10:11], v[2:3], v[6:7]
	v_pk_mul_f32 v[6:7], v[82:83], v[46:47] op_sel_hi:[0,1]
	v_lshlrev_b32_e32 v58, 16, v32
	v_and_b32_e32 v59, 0xffff0000, v32
	v_pk_fma_f32 v[2:3], v[34:35], v[6:7], v[2:3]
	v_pk_mul_f32 v[6:7], v[84:85], v[54:55] op_sel_hi:[0,1]
	v_pk_fma_f32 v[2:3], v[66:67], v[6:7], v[2:3]
	v_pk_mul_f32 v[6:7], v[86:87], v[58:59] op_sel_hi:[0,1]
	v_pk_fma_f32 v[2:3], v[78:79], v[6:7], v[2:3]
	v_lshlrev_b32_e32 v4, 16, v5
	v_mul_f32_e32 v6, 0xbfb8aa3b, v2
	v_mul_f32_e32 v7, 0xbfb8aa3b, v3
	v_exp_f32_e32 v6, v6
	v_exp_f32_e32 v7, v7
	v_and_b32_e32 v5, 0xffff0000, v5
	v_lshlrev_b32_e32 v24, 16, v25
	v_add_f32_e32 v6, 1.0, v6
	v_add_f32_e32 v7, 1.0, v7
	v_rcp_f32_e32 v6, v6
	v_rcp_f32_e32 v7, v7
	v_and_b32_e32 v25, 0xffff0000, v25
	v_lshlrev_b32_e32 v28, 16, v29
	v_and_b32_e32 v29, 0xffff0000, v29
	v_pk_mul_f32 v[6:7], v[2:3], v[6:7]
	v_pk_mul_f32 v[2:3], v[0:1], v[4:5] op_sel_hi:[0,1]
	v_pk_fma_f32 v[2:3], v[12:13], v[2:3], v[8:9]
	v_pk_mul_f32 v[4:5], v[82:83], v[24:25] op_sel_hi:[0,1]
	v_lshlrev_b32_e32 v32, 16, v33
	v_and_b32_e32 v33, 0xffff0000, v33
	v_pk_fma_f32 v[2:3], v[36:37], v[4:5], v[2:3]
	v_pk_mul_f32 v[4:5], v[84:85], v[28:29] op_sel_hi:[0,1]
	v_pk_fma_f32 v[2:3], v[68:69], v[4:5], v[2:3]
	v_pk_mul_f32 v[4:5], v[86:87], v[32:33] op_sel_hi:[0,1]
	v_pk_fma_f32 v[2:3], v[80:81], v[4:5], v[2:3]
	v_pk_mul_f32 v[40:41], v[0:1], v[40:41] op_sel_hi:[0,1]
	v_mul_f32_e32 v0, 0xbfb8aa3b, v2
	v_exp_f32_e32 v0, v0
	v_pk_fma_f32 v[14:15], v[18:19], v[40:41], v[14:15]
	v_pk_mul_f32 v[18:19], v[82:83], v[44:45] op_sel_hi:[0,1]
	v_pk_fma_f32 v[14:15], v[50:51], v[18:19], v[14:15]
	v_pk_mul_f32 v[18:19], v[84:85], v[48:49] op_sel_hi:[0,1]
	v_pk_fma_f32 v[14:15], v[70:71], v[18:19], v[14:15]
	v_pk_mul_f32 v[18:19], v[86:87], v[56:57] op_sel_hi:[0,1]
	v_pk_fma_f32 v[14:15], v[74:75], v[18:19], v[14:15]
	v_add_f32_e32 v0, 1.0, v0
	v_mul_f32_e32 v18, 0xbfb8aa3b, v14
	v_mul_f32_e32 v19, 0xbfb8aa3b, v15
	v_rcp_f32_e32 v4, v0
	v_mul_f32_e32 v0, 0xbfb8aa3b, v3
	v_exp_f32_e32 v18, v18
	v_exp_f32_e32 v19, v19
	v_exp_f32_e32 v0, v0
	v_lshlrev_b32_e32 v26, 7, v126
	v_add_f32_e32 v18, 1.0, v18
	v_add_f32_e32 v19, 1.0, v19
	v_add_f32_e32 v0, 1.0, v0
	v_rcp_f32_e32 v18, v18
	v_rcp_f32_e32 v19, v19
	v_rcp_f32_e32 v5, v0
	v_lshlrev_b32_e32 v0, 5, v126
	v_bitop3_b32 v28, v0, v135, s95 bitop3:0x6c
	v_pk_mul_f32 v[14:15], v[14:15], v[18:19]
	v_pk_mul_f32 v[8:9], v[2:3], v[4:5]
	v_cvt_pk_bf16_f32 v2, v14, v15
	v_cvt_pk_bf16_f32 v3, v16, v17
	v_cvt_pk_bf16_f32 v4, v6, v7
	v_cvt_pk_bf16_f32 v5, v8, v9
	ds_write_b128 v38, v[2:5] offset:17408
	v_mad_i64_i32 v[2:3], s[40:41], v83, s89, v[100:101]
	v_lshl_add_u64 v[2:3], v[2:3], 0, s[16:17]
	v_lshl_add_u64 v[2:3], v[2:3], 0, v[98:99]
	v_and_b32_e32 v4, 0x60, v0
	v_bitop3_b32 v0, v4, v26, v135 bitop3:0xde
	global_load_dwordx4 v[2:5], v[2:3], off offset:2880
	v_lshlrev_b32_e32 v0, 1, v0
	v_ashrrev_i32_e32 v27, 31, v26
	s_ashr_i32 s16, s94, 7
	s_lshl_b32 s0, s16, 6
	v_lshlrev_b32_e32 v23, 6, v129
	v_and_b32_e32 v29, 0xb00, v23
	s_waitcnt vmcnt(0)
	ds_write_b128 v0, v[2:5] offset:34816
	v_lshl_add_u64 v[2:3], v[26:27], 1, v[114:115]
	global_load_dwordx4 v[2:5], v[2:3], off
	v_add_u32_e32 v26, 0x2000, v26
	s_waitcnt vmcnt(0)
	ds_write_b128 v0, v[2:5] offset:51200
	v_and_b32_e32 v2, 16, v129
	v_lshlrev_b32_e32 v0, 4, v130
	v_and_or_b32 v2, v131, 12, v2
	v_mad_u32_u24 v127, v121, s28, v0
	v_mad_u32_u24 v0, v133, s28, v0
	v_or_b32_e32 v125, s0, v2
	v_and_b32_e32 v3, 0x60, v134
	s_waitcnt lgkmcnt(0)
	s_barrier
	v_bitop3_b32 v22, v2, v3, s0 bitop3:0x36
	v_bitop3_b32 v27, v125, v3, 32 bitop3:0x36
	ds_read_b128 v[18:21], v0 offset:26112
	ds_read_b128 v[34:37], v127
	ds_read_b128 v[66:69], v127 offset:32
	ds_read_b128 v[2:5], v0 offset:17408
	ds_read_b128 v[30:33], v0 offset:17440
	s_waitcnt lgkmcnt(1)
	v_mfma_f32_32x32x16_bf16 v[2:17], v[2:5], v[34:37], 0
	v_lshl_add_u32 v131, v22, 1, v29
	v_lshl_add_u32 v133, v27, 1, v29
	ds_read_b64_tr_b16 v[22:23], v131 offset:51200
	ds_read_b64_tr_b16 v[24:25], v131 offset:52224
	ds_read_b64_tr_b16 v[38:39], v133 offset:51200
	ds_read_b64_tr_b16 v[40:41], v133 offset:52224
	ds_read_b128 v[98:101], v0 offset:26144
	v_lshlrev_b32_e32 v27, 8, v132
	v_lshl_or_b32 v27, v122, 1, v27
	v_lshlrev_b32_e32 v29, 8, v126
	s_waitcnt lgkmcnt(5)
	v_mfma_f32_32x32x16_bf16 v[2:17], v[30:33], v[66:69], v[2:17]
	ds_read_b64_tr_b16 v[110:111], v131 offset:55296
	ds_read_b64_tr_b16 v[112:113], v131 offset:56320
	ds_read_b64_tr_b16 v[102:103], v133 offset:55296
	ds_read_b64_tr_b16 v[104:105], v133 offset:56320
	ds_read_b128 v[74:77], v127 offset:64
	ds_read_b128 v[30:33], v0 offset:17472
	ds_read_b128 v[106:109], v0 offset:26176
	s_waitcnt lgkmcnt(1)
	v_mfma_f32_32x32x16_bf16 v[2:17], v[30:33], v[74:77], v[2:17]
	ds_read_b64_tr_b16 v[90:91], v131 offset:59392
	ds_read_b64_tr_b16 v[92:93], v131 offset:60416
	ds_read_b64_tr_b16 v[82:83], v133 offset:59392
	ds_read_b64_tr_b16 v[84:85], v133 offset:60416
	ds_read_b128 v[70:73], v127 offset:96
	ds_read_b128 v[30:33], v0 offset:17504
	ds_read_b128 v[94:97], v0 offset:26208
	ds_read_b64_tr_b16 v[86:87], v131 offset:63488
	ds_read_b64_tr_b16 v[88:89], v131 offset:64512
	ds_read_b64_tr_b16 v[78:79], v133 offset:63488
	ds_read_b64_tr_b16 v[80:81], v133 offset:64512
	s_waitcnt lgkmcnt(0)
	s_barrier
	v_mfma_f32_32x32x16_bf16 v[2:17], v[30:33], v[70:73], v[2:17]
	v_add_u32_e32 v210, 0x2000, v116
	v_ashrrev_i32_e32 v211, 31, v210
	v_lshl_add_u64 v[210:211], v[210:211], 1, v[114:115]
	global_load_dwordx4 v[210:213], v[210:211], off
	v_add_u32_e32 v214, 0x2000, v118
	v_ashrrev_i32_e32 v215, 31, v214
	v_lshl_add_u64 v[214:215], v[214:215], 1, v[114:115]
	global_load_dwordx4 v[214:217], v[214:215], off
	v_add_u32_e32 v218, 0x2000, v120
	v_ashrrev_i32_e32 v219, 31, v218
	v_lshl_add_u64 v[218:219], v[218:219], 1, v[114:115]
	global_load_dwordx4 v[218:221], v[218:219], off
	v_mov_b32_e32 v222, v26
	v_ashrrev_i32_e32 v223, 31, v26
	v_lshl_add_u64 v[222:223], v[222:223], 1, v[114:115]
	global_load_dwordx4 v[222:225], v[222:223], off
	v_lshlrev_b32_e32 v116, 2, v130
	v_cmp_le_u32_e32 vcc, v116, v121
	s_waitcnt vmcnt(3)
	ds_write_b128 v27, v[210:213] offset:51200
	v_lshlrev_b32_e32 v27, 8, v117
	v_lshl_or_b32 v27, v123, 1, v27
	v_mfma_f32_32x32x16_bf16 v[50:65], v[18:21], v[34:37], 0
	v_lshlrev_b32_e32 v117, 2, v121
	s_waitcnt vmcnt(2)
	ds_write_b128 v27, v[214:217] offset:51200
	v_lshlrev_b32_e32 v27, 8, v119
	v_lshl_or_b32 v27, v124, 1, v27
	v_mfma_f32_32x32x16_bf16 v[50:65], v[98:101], v[66:69], v[50:65]
	v_mov_b32_e32 v120, 0
	s_waitcnt vmcnt(1)
	ds_write_b128 v27, v[218:221] offset:51200
	v_lshl_or_b32 v30, v28, 1, v29
	v_mfma_f32_32x32x16_bf16 v[50:65], v[106:109], v[74:77], v[50:65]
	v_mov_b32_e32 v115, 0
	s_waitcnt vmcnt(0)
	ds_write_b128 v30, v[222:225] offset:51200
	v_mfma_f32_32x32x16_bf16 v[18:33], v[22:25], v[34:37], 0
	s_waitcnt lgkmcnt(0)
	s_barrier
	v_mfma_f32_32x32x16_bf16 v[34:49], v[38:41], v[34:37], 0
	v_mfma_f32_32x32x16_bf16 v[18:33], v[110:113], v[66:69], v[18:33]
	v_mfma_f32_32x32x16_bf16 v[34:49], v[102:105], v[66:69], v[34:49]
	v_mfma_f32_32x32x16_bf16 v[18:33], v[90:93], v[74:77], v[18:33]
	v_mfma_f32_32x32x16_bf16 v[34:49], v[82:85], v[74:77], v[34:49]
	v_mfma_f32_32x32x16_bf16 v[50:65], v[94:97], v[70:73], v[50:65]
	v_mfma_f32_32x32x16_bf16 v[18:33], v[86:89], v[70:73], v[18:33]
	v_mfma_f32_32x32x16_bf16 v[34:49], v[78:81], v[70:73], v[34:49]
	ds_read_b128 v[70:73], v127 offset:128
	ds_read_b128 v[66:69], v127 offset:160
	ds_read_b128 v[74:77], v0 offset:26240
	ds_read_b128 v[78:81], v0 offset:17536
	ds_read_b128 v[82:85], v0 offset:17568
	s_waitcnt lgkmcnt(1)
	v_mfma_f32_32x32x16_bf16 v[2:17], v[78:81], v[70:73], v[2:17]
	v_mfma_f32_32x32x16_bf16 v[50:65], v[74:77], v[70:73], v[50:65]
	ds_read_b64_tr_b16 v[74:75], v131 offset:51200
	ds_read_b64_tr_b16 v[76:77], v131 offset:52224
	ds_read_b64_tr_b16 v[98:99], v133 offset:51200
	ds_read_b64_tr_b16 v[100:101], v133 offset:52224
	ds_read_b128 v[78:81], v0 offset:26272
	s_waitcnt lgkmcnt(5)
	v_mfma_f32_32x32x16_bf16 v[2:17], v[82:85], v[66:69], v[2:17]
	s_waitcnt lgkmcnt(0)
	v_mfma_f32_32x32x16_bf16 v[50:65], v[78:81], v[66:69], v[50:65]
	ds_read_b64_tr_b16 v[90:91], v131 offset:55296
	ds_read_b64_tr_b16 v[92:93], v131 offset:56320
	ds_read_b64_tr_b16 v[102:103], v133 offset:55296
	ds_read_b64_tr_b16 v[104:105], v133 offset:56320
	ds_read_b128 v[78:81], v127 offset:192
	ds_read_b128 v[82:85], v0 offset:17600
	ds_read_b128 v[86:89], v0 offset:26304
	s_waitcnt lgkmcnt(1)
	v_mfma_f32_32x32x16_bf16 v[2:17], v[82:85], v[78:81], v[2:17]
	s_waitcnt lgkmcnt(0)
	v_mfma_f32_32x32x16_bf16 v[50:65], v[86:89], v[78:81], v[50:65]
	ds_read_b64_tr_b16 v[94:95], v131 offset:59392
	ds_read_b64_tr_b16 v[96:97], v131 offset:60416
	ds_read_b64_tr_b16 v[106:107], v133 offset:59392
	ds_read_b64_tr_b16 v[108:109], v133 offset:60416
	ds_read_b128 v[82:85], v127 offset:224
	ds_read_b128 v[86:89], v0 offset:17632
	ds_read_b128 v[110:113], v0 offset:26336
	v_or_b32_e32 v0, 0x10800, v117
	s_waitcnt lgkmcnt(1)
	v_mfma_f32_32x32x16_bf16 v[2:17], v[86:89], v[82:85], v[2:17]
	s_waitcnt lgkmcnt(0)
	v_mfma_f32_32x32x16_bf16 v[50:65], v[110:113], v[82:85], v[50:65]
	ds_read_b64_tr_b16 v[86:87], v131 offset:63488
	ds_read_b64_tr_b16 v[88:89], v131 offset:64512
	ds_read_b64_tr_b16 v[110:111], v133 offset:63488
	ds_read_b64_tr_b16 v[112:113], v133 offset:64512
	ds_read_b32 v114, v0
	v_or_b32_e32 v0, 0x10a00, v117
	ds_read_b32 v118, v0
	v_or_b32_e32 v0, 0x10b00, v117
	ds_read_b32 v0, v0
	s_waitcnt lgkmcnt(1)
	v_sub_f32_e32 v119, v114, v118
	s_and_saveexec_b64 s[40:41], vcc
	s_cbranch_execz .LBB0_411
	v_lshl_or_b32 v114, v116, 2, v182
	ds_read_b32 v114, v114
	s_waitcnt lgkmcnt(0)
	v_add_f32_e32 v114, v119, v114
	v_mul_f32_e32 v114, 0x3fb8aa3b, v114
	v_exp_f32_e32 v120, v114

	.amdhsa_kernel _Z14fwd_megakernel6Params
		.amdhsa_group_segment_fixed_size 78368
		.amdhsa_private_segment_fixed_size 0
		.amdhsa_kernarg_size 440
		.amdhsa_user_sgpr_count 2
		.amdhsa_user_sgpr_dispatch_ptr 0
		.amdhsa_user_sgpr_queue_ptr 0
		.amdhsa_user_sgpr_kernarg_segment_ptr 1
		.amdhsa_user_sgpr_dispatch_id 0
		.amdhsa_user_sgpr_kernarg_preload_length 0
		.amdhsa_user_sgpr_kernarg_preload_offset 0
		.amdhsa_user_sgpr_private_segment_size 0
		.amdhsa_uses_dynamic_stack 0
		.amdhsa_enable_private_segment 0
		.amdhsa_system_sgpr_workgroup_id_x 1
		.amdhsa_system_sgpr_workgroup_id_y 0
		.amdhsa_system_sgpr_workgroup_id_z 0
		.amdhsa_system_sgpr_workgroup_info 0
		.amdhsa_system_vgpr_workitem_id 2
		.amdhsa_next_free_vgpr 239
		.amdhsa_next_free_sgpr 102
		.amdhsa_accum_offset 240
		.amdhsa_reserve_vcc 1
		.amdhsa_float_round_mode_32 0
		.amdhsa_float_round_mode_16_64 0
		.amdhsa_float_denorm_mode_32 3
		.amdhsa_float_denorm_mode_16_64 3
		.amdhsa_dx10_clamp 1
		.amdhsa_ieee_mode 1
		.amdhsa_fp16_overflow 0
		.amdhsa_tg_split 0
		.amdhsa_exception_fp_ieee_invalid_op 0
		.amdhsa_exception_fp_denorm_src 0
		.amdhsa_exception_fp_ieee_div_zero 0
		.amdhsa_exception_fp_ieee_overflow 0
		.amdhsa_exception_fp_ieee_underflow 0
		.amdhsa_exception_fp_ieee_inexact 0
		.amdhsa_exception_int_div_zero 0
	.end_amdhsa_kernel

amdhsa.kernels:
  - .agpr_count:     0
    .args:
      - .offset:         0
        .size:           184
        .value_kind:     by_value
      - .offset:         184
        .size:           4
        .value_kind:     hidden_block_count_x
      - .offset:         188
        .size:           4
        .value_kind:     hidden_block_count_y
      - .offset:         192
        .size:           4
        .value_kind:     hidden_block_count_z
      - .offset:         196
        .size:           2
        .value_kind:     hidden_group_size_x
      - .offset:         198
        .size:           2
        .value_kind:     hidden_group_size_y
      - .offset:         200
        .size:           2
        .value_kind:     hidden_group_size_z
      - .offset:         202
        .size:           2
        .value_kind:     hidden_remainder_x
      - .offset:         204
        .size:           2
        .value_kind:     hidden_remainder_y
      - .offset:         206
        .size:           2
        .value_kind:     hidden_remainder_z
      - .offset:         224
        .size:           8
        .value_kind:     hidden_global_offset_x
      - .offset:         232
        .size:           8
        .value_kind:     hidden_global_offset_y
      - .offset:         240
        .size:           8
        .value_kind:     hidden_global_offset_z
      - .offset:         248
        .size:           2
        .value_kind:     hidden_grid_dims
      - .offset:         272
        .size:           8
        .value_kind:     hidden_multigrid_sync_arg
    .group_segment_fixed_size: 78368
    .kernarg_segment_align: 8
    .kernarg_segment_size: 440
    .language:       OpenCL C
    .language_version:
      - 2
      - 0
    .max_flat_workgroup_size: 256
    .name:           _Z14fwd_megakernel6Params
    .private_segment_fixed_size: 0
    .sgpr_count:     108
    .sgpr_spill_count: 165
    .symbol:         _Z14fwd_megakernel6Params.kd
    .uniform_work_group_size: 1
    .uses_dynamic_stack: false
    .vgpr_count:     239
    .vgpr_spill_count: 0
    .wavefront_size: 64
